# GU epilogue rewritten by hand: batched reductions, packed ops over two row groups at a time, 32-bit store offsets (same per-element op order)
# speedup vs baseline: 1.0121x; 1.0121x over previous
.LBB0_1106:
	s_lshl_b32 s0, s29, 8
	s_add_i32 s0, s0, s77
	v_and_or_b32 v160, v193, 15, s0
	v_bfe_u32 v180, v193, 4, 2
	v_add_f32_e32 v130, v195, v194
	v_add_f32_e32 v146, v196, v197
	v_add_f32_e32 v131, v199, v198
	v_add_f32_e32 v147, v200, v201
	v_add_f32_e32 v132, v203, v202
	v_add_f32_e32 v148, v204, v205
	v_add_f32_e32 v133, v207, v206
	v_add_f32_e32 v149, v208, v209
	v_add_f32_e32 v130, v130, v146
	v_add_f32_e32 v131, v131, v147
	v_add_f32_e32 v132, v132, v148
	v_add_f32_e32 v133, v133, v149
	ds_swizzle_b32 v146, v221 offset:swizzle(SWAP,16)
	ds_swizzle_b32 v147, v222 offset:swizzle(SWAP,16)
	ds_swizzle_b32 v148, v223 offset:swizzle(SWAP,16)
	ds_swizzle_b32 v149, v224 offset:swizzle(SWAP,16)
	ds_swizzle_b32 v150, v130 offset:swizzle(SWAP,16)
	ds_swizzle_b32 v151, v131 offset:swizzle(SWAP,16)
	ds_swizzle_b32 v152, v132 offset:swizzle(SWAP,16)
	ds_swizzle_b32 v153, v133 offset:swizzle(SWAP,16)
	s_lshl_b32 s0, s28, 7
	v_lshl_or_b32 v218, v180, 3, s0
	v_or_b32_e32 v218, s78, v218
	v_mul_lo_u32 v161, v160, s70
	v_lshl_add_u32 v161, v218, 1, v161
	s_waitcnt lgkmcnt(0)
	v_add_f32_e32 v154, v221, v146
	v_add_f32_e32 v155, v222, v147
	v_add_f32_e32 v156, v223, v148
	v_add_f32_e32 v157, v224, v149
	v_add_f32_e32 v158, v130, v150
	v_add_f32_e32 v159, v131, v151
	v_add_f32_e32 v162, v132, v152
	v_add_f32_e32 v163, v133, v153
	v_mov_b32_e32 v164, v154
	v_mov_b32_e32 v165, v155
	v_mov_b32_e32 v166, v156
	v_mov_b32_e32 v167, v157
	v_mov_b32_e32 v168, v158
	v_mov_b32_e32 v169, v159
	v_mov_b32_e32 v170, v162
	v_mov_b32_e32 v171, v163
	v_permlane32_swap_b32_e32 v154, v164
	v_permlane32_swap_b32_e32 v155, v165
	v_permlane32_swap_b32_e32 v156, v166
	v_permlane32_swap_b32_e32 v157, v167
	v_permlane32_swap_b32_e32 v158, v168
	v_permlane32_swap_b32_e32 v159, v169
	v_permlane32_swap_b32_e32 v162, v170
	v_permlane32_swap_b32_e32 v163, v171
	v_add_f32_e32 v154, v154, v164
	v_add_f32_e32 v155, v155, v165
	v_add_f32_e32 v156, v156, v166
	v_add_f32_e32 v157, v157, v167
	v_add_f32_e32 v158, v158, v168
	v_add_f32_e32 v159, v159, v169
	v_add_f32_e32 v162, v162, v170
	v_add_f32_e32 v163, v163, v171
	v_fma_f32 v154, v154, s62, v192
	v_fma_f32 v155, v155, s62, v192
	v_fma_f32 v156, v156, s62, v192
	v_fma_f32 v157, v157, s62, v192
	v_fma_f32 v158, v158, s62, v192
	v_fma_f32 v159, v159, s62, v192
	v_fma_f32 v162, v162, s62, v192
	v_fma_f32 v163, v163, s62, v192
	v_rsq_f32_e32 v154, v154
	v_rsq_f32_e32 v155, v155
	v_rsq_f32_e32 v156, v156
	v_rsq_f32_e32 v157, v157
	v_rsq_f32_e32 v158, v158
	v_rsq_f32_e32 v159, v159
	v_rsq_f32_e32 v162, v162
	v_rsq_f32_e32 v163, v163
	v_mul_f32_e32 v172, 0xbfb8aa3b, v154
	v_mul_f32_e32 v174, 0xbfb8aa3b, v155
	v_mul_f32_e32 v176, 0xbfb8aa3b, v156
	v_mul_f32_e32 v182, 0xbfb8aa3b, v157
	v_mul_f32_e32 v184, 0xbfb8aa3b, v158
	v_mul_f32_e32 v186, 0xbfb8aa3b, v159
	v_mul_f32_e32 v188, 0xbfb8aa3b, v162
	v_mul_f32_e32 v190, 0xbfb8aa3b, v163
	v_mul_f32_e32 v173, v154, v154
	v_mul_f32_e32 v175, v155, v155
	v_mul_f32_e32 v177, v156, v156
	v_mul_f32_e32 v183, v157, v157
	v_mul_f32_e32 v185, v158, v158
	v_mul_f32_e32 v187, v159, v159
	v_mul_f32_e32 v189, v162, v162
	v_mul_f32_e32 v191, v163, v163
	v_pk_mul_f32 v[228:229], v[122:123], v[172:173] op_sel_hi:[1,0]
	v_pk_mul_f32 v[230:231], v[124:125], v[172:173] op_sel_hi:[1,0]
	v_pk_mul_f32 v[232:233], v[114:115], v[172:173] op_sel_hi:[1,0]
	v_pk_mul_f32 v[234:235], v[116:117], v[172:173] op_sel_hi:[1,0]
	v_pk_mul_f32 v[236:237], v[106:107], v[174:175] op_sel_hi:[1,0]
	v_pk_mul_f32 v[238:239], v[108:109], v[174:175] op_sel_hi:[1,0]
	v_pk_mul_f32 v[240:241], v[98:99], v[174:175] op_sel_hi:[1,0]
	v_pk_mul_f32 v[242:243], v[100:101], v[174:175] op_sel_hi:[1,0]
	v_exp_f32_e32 v228, v228
	v_exp_f32_e32 v229, v229
	v_exp_f32_e32 v230, v230
	v_exp_f32_e32 v231, v231
	v_exp_f32_e32 v232, v232
	v_exp_f32_e32 v233, v233
	v_exp_f32_e32 v234, v234
	v_exp_f32_e32 v235, v235
	v_exp_f32_e32 v236, v236
	v_exp_f32_e32 v237, v237
	v_exp_f32_e32 v238, v238
	v_exp_f32_e32 v239, v239
	v_exp_f32_e32 v240, v240
	v_exp_f32_e32 v241, v241
	v_exp_f32_e32 v242, v242
	v_exp_f32_e32 v243, v243
	v_pk_add_f32 v[228:229], v[228:229], 1.0 op_sel_hi:[1,0]
	v_pk_add_f32 v[230:231], v[230:231], 1.0 op_sel_hi:[1,0]
	v_pk_add_f32 v[232:233], v[232:233], 1.0 op_sel_hi:[1,0]
	v_pk_add_f32 v[234:235], v[234:235], 1.0 op_sel_hi:[1,0]
	v_pk_add_f32 v[236:237], v[236:237], 1.0 op_sel_hi:[1,0]
	v_pk_add_f32 v[238:239], v[238:239], 1.0 op_sel_hi:[1,0]
	v_pk_add_f32 v[240:241], v[240:241], 1.0 op_sel_hi:[1,0]
	v_pk_add_f32 v[242:243], v[242:243], 1.0 op_sel_hi:[1,0]
	v_pk_mul_f32 v[122:123], v[122:123], v[126:127]
	v_pk_mul_f32 v[124:125], v[124:125], v[128:129]
	v_pk_mul_f32 v[114:115], v[114:115], v[118:119]
	v_pk_mul_f32 v[116:117], v[116:117], v[120:121]
	v_pk_mul_f32 v[106:107], v[106:107], v[110:111]
	v_pk_mul_f32 v[108:109], v[108:109], v[112:113]
	v_pk_mul_f32 v[98:99], v[98:99], v[102:103]
	v_pk_mul_f32 v[100:101], v[100:101], v[104:105]
	v_rcp_f32_e32 v228, v228
	v_rcp_f32_e32 v229, v229
	v_rcp_f32_e32 v230, v230
	v_rcp_f32_e32 v231, v231
	v_rcp_f32_e32 v232, v232
	v_rcp_f32_e32 v233, v233
	v_rcp_f32_e32 v234, v234
	v_rcp_f32_e32 v235, v235
	v_rcp_f32_e32 v236, v236
	v_rcp_f32_e32 v237, v237
	v_rcp_f32_e32 v238, v238
	v_rcp_f32_e32 v239, v239
	v_rcp_f32_e32 v240, v240
	v_rcp_f32_e32 v241, v241
	v_rcp_f32_e32 v242, v242
	v_rcp_f32_e32 v243, v243
	v_pk_mul_f32 v[228:229], v[172:173], v[228:229] op_sel:[1,0] op_sel_hi:[1,1]
	v_pk_mul_f32 v[230:231], v[172:173], v[230:231] op_sel:[1,0] op_sel_hi:[1,1]
	v_pk_mul_f32 v[232:233], v[172:173], v[232:233] op_sel:[1,0] op_sel_hi:[1,1]
	v_pk_mul_f32 v[234:235], v[172:173], v[234:235] op_sel:[1,0] op_sel_hi:[1,1]
	v_pk_mul_f32 v[236:237], v[174:175], v[236:237] op_sel:[1,0] op_sel_hi:[1,1]
	v_pk_mul_f32 v[238:239], v[174:175], v[238:239] op_sel:[1,0] op_sel_hi:[1,1]
	v_pk_mul_f32 v[240:241], v[174:175], v[240:241] op_sel:[1,0] op_sel_hi:[1,1]
	v_pk_mul_f32 v[242:243], v[174:175], v[242:243] op_sel:[1,0] op_sel_hi:[1,1]
	v_pk_mul_f32 v[228:229], v[122:123], v[228:229]
	v_pk_mul_f32 v[230:231], v[124:125], v[230:231]
	v_pk_mul_f32 v[232:233], v[114:115], v[232:233]
	v_pk_mul_f32 v[234:235], v[116:117], v[234:235]
	v_pk_mul_f32 v[236:237], v[106:107], v[236:237]
	v_pk_mul_f32 v[238:239], v[108:109], v[238:239]
	v_pk_mul_f32 v[240:241], v[98:99], v[240:241]
	v_pk_mul_f32 v[242:243], v[100:101], v[242:243]
	v_add_u32_e32 v218, 0x0, v161
	v_add_u32_e32 v219, 0x16000, v161
	v_cvt_pk_bf16_f32 v244, v228, v229
	v_cvt_pk_bf16_f32 v245, v230, v231
	v_cvt_pk_bf16_f32 v246, v232, v233
	v_cvt_pk_bf16_f32 v247, v234, v235
	v_cvt_pk_bf16_f32 v214, v236, v237
	v_cvt_pk_bf16_f32 v215, v238, v239
	v_cvt_pk_bf16_f32 v216, v240, v241
	v_cvt_pk_bf16_f32 v217, v242, v243
	global_store_dwordx4 v218, v[244:247], s[8:9]
	global_store_dwordx4 v219, v[214:217], s[8:9]
	v_pk_mul_f32 v[228:229], v[90:91], v[176:177] op_sel_hi:[1,0]
	v_pk_mul_f32 v[230:231], v[92:93], v[176:177] op_sel_hi:[1,0]
	v_pk_mul_f32 v[232:233], v[82:83], v[176:177] op_sel_hi:[1,0]
	v_pk_mul_f32 v[234:235], v[84:85], v[176:177] op_sel_hi:[1,0]
	v_pk_mul_f32 v[236:237], v[74:75], v[182:183] op_sel_hi:[1,0]
	v_pk_mul_f32 v[238:239], v[76:77], v[182:183] op_sel_hi:[1,0]
	v_pk_mul_f32 v[240:241], v[66:67], v[182:183] op_sel_hi:[1,0]
	v_pk_mul_f32 v[242:243], v[68:69], v[182:183] op_sel_hi:[1,0]
	v_exp_f32_e32 v228, v228
	v_exp_f32_e32 v229, v229
	v_exp_f32_e32 v230, v230
	v_exp_f32_e32 v231, v231
	v_exp_f32_e32 v232, v232
	v_exp_f32_e32 v233, v233
	v_exp_f32_e32 v234, v234
	v_exp_f32_e32 v235, v235
	v_exp_f32_e32 v236, v236
	v_exp_f32_e32 v237, v237
	v_exp_f32_e32 v238, v238
	v_exp_f32_e32 v239, v239
	v_exp_f32_e32 v240, v240
	v_exp_f32_e32 v241, v241
	v_exp_f32_e32 v242, v242
	v_exp_f32_e32 v243, v243
	v_pk_add_f32 v[228:229], v[228:229], 1.0 op_sel_hi:[1,0]
	v_pk_add_f32 v[230:231], v[230:231], 1.0 op_sel_hi:[1,0]
	v_pk_add_f32 v[232:233], v[232:233], 1.0 op_sel_hi:[1,0]
	v_pk_add_f32 v[234:235], v[234:235], 1.0 op_sel_hi:[1,0]
	v_pk_add_f32 v[236:237], v[236:237], 1.0 op_sel_hi:[1,0]
	v_pk_add_f32 v[238:239], v[238:239], 1.0 op_sel_hi:[1,0]
	v_pk_add_f32 v[240:241], v[240:241], 1.0 op_sel_hi:[1,0]
	v_pk_add_f32 v[242:243], v[242:243], 1.0 op_sel_hi:[1,0]
	v_pk_mul_f32 v[90:91], v[90:91], v[94:95]
	v_pk_mul_f32 v[92:93], v[92:93], v[96:97]
	v_pk_mul_f32 v[82:83], v[82:83], v[86:87]
	v_pk_mul_f32 v[84:85], v[84:85], v[88:89]
	v_pk_mul_f32 v[74:75], v[74:75], v[78:79]
	v_pk_mul_f32 v[76:77], v[76:77], v[80:81]
	v_pk_mul_f32 v[66:67], v[66:67], v[70:71]
	v_pk_mul_f32 v[68:69], v[68:69], v[72:73]
	v_rcp_f32_e32 v228, v228
	v_rcp_f32_e32 v229, v229
	v_rcp_f32_e32 v230, v230
	v_rcp_f32_e32 v231, v231
	v_rcp_f32_e32 v232, v232
	v_rcp_f32_e32 v233, v233
	v_rcp_f32_e32 v234, v234
	v_rcp_f32_e32 v235, v235
	v_rcp_f32_e32 v236, v236
	v_rcp_f32_e32 v237, v237
	v_rcp_f32_e32 v238, v238
	v_rcp_f32_e32 v239, v239
	v_rcp_f32_e32 v240, v240
	v_rcp_f32_e32 v241, v241
	v_rcp_f32_e32 v242, v242
	v_rcp_f32_e32 v243, v243
	v_pk_mul_f32 v[228:229], v[176:177], v[228:229] op_sel:[1,0] op_sel_hi:[1,1]
	v_pk_mul_f32 v[230:231], v[176:177], v[230:231] op_sel:[1,0] op_sel_hi:[1,1]
	v_pk_mul_f32 v[232:233], v[176:177], v[232:233] op_sel:[1,0] op_sel_hi:[1,1]
	v_pk_mul_f32 v[234:235], v[176:177], v[234:235] op_sel:[1,0] op_sel_hi:[1,1]
	v_pk_mul_f32 v[236:237], v[182:183], v[236:237] op_sel:[1,0] op_sel_hi:[1,1]
	v_pk_mul_f32 v[238:239], v[182:183], v[238:239] op_sel:[1,0] op_sel_hi:[1,1]
	v_pk_mul_f32 v[240:241], v[182:183], v[240:241] op_sel:[1,0] op_sel_hi:[1,1]
	v_pk_mul_f32 v[242:243], v[182:183], v[242:243] op_sel:[1,0] op_sel_hi:[1,1]
	v_pk_mul_f32 v[228:229], v[90:91], v[228:229]
	v_pk_mul_f32 v[230:231], v[92:93], v[230:231]
	v_pk_mul_f32 v[232:233], v[82:83], v[232:233]
	v_pk_mul_f32 v[234:235], v[84:85], v[234:235]
	v_pk_mul_f32 v[236:237], v[74:75], v[236:237]
	v_pk_mul_f32 v[238:239], v[76:77], v[238:239]
	v_pk_mul_f32 v[240:241], v[66:67], v[240:241]
	v_pk_mul_f32 v[242:243], v[68:69], v[242:243]
	v_add_u32_e32 v218, 0x2c000, v161
	v_add_u32_e32 v219, 0x42000, v161
	v_cvt_pk_bf16_f32 v244, v228, v229
	v_cvt_pk_bf16_f32 v245, v230, v231
	v_cvt_pk_bf16_f32 v246, v232, v233
	v_cvt_pk_bf16_f32 v247, v234, v235
	v_cvt_pk_bf16_f32 v214, v236, v237
	v_cvt_pk_bf16_f32 v215, v238, v239
	v_cvt_pk_bf16_f32 v216, v240, v241
	v_cvt_pk_bf16_f32 v217, v242, v243
	global_store_dwordx4 v218, v[244:247], s[8:9]
	global_store_dwordx4 v219, v[214:217], s[8:9]
	v_pk_mul_f32 v[228:229], v[58:59], v[184:185] op_sel_hi:[1,0]
	v_pk_mul_f32 v[230:231], v[60:61], v[184:185] op_sel_hi:[1,0]
	v_pk_mul_f32 v[232:233], v[50:51], v[184:185] op_sel_hi:[1,0]
	v_pk_mul_f32 v[234:235], v[52:53], v[184:185] op_sel_hi:[1,0]
	v_pk_mul_f32 v[236:237], v[42:43], v[186:187] op_sel_hi:[1,0]
	v_pk_mul_f32 v[238:239], v[44:45], v[186:187] op_sel_hi:[1,0]
	v_pk_mul_f32 v[240:241], v[34:35], v[186:187] op_sel_hi:[1,0]
	v_pk_mul_f32 v[242:243], v[36:37], v[186:187] op_sel_hi:[1,0]
	v_exp_f32_e32 v228, v228
	v_exp_f32_e32 v229, v229
	v_exp_f32_e32 v230, v230
	v_exp_f32_e32 v231, v231
	v_exp_f32_e32 v232, v232
	v_exp_f32_e32 v233, v233
	v_exp_f32_e32 v234, v234
	v_exp_f32_e32 v235, v235
	v_exp_f32_e32 v236, v236
	v_exp_f32_e32 v237, v237
	v_exp_f32_e32 v238, v238
	v_exp_f32_e32 v239, v239
	v_exp_f32_e32 v240, v240
	v_exp_f32_e32 v241, v241
	v_exp_f32_e32 v242, v242
	v_exp_f32_e32 v243, v243
	v_pk_add_f32 v[228:229], v[228:229], 1.0 op_sel_hi:[1,0]
	v_pk_add_f32 v[230:231], v[230:231], 1.0 op_sel_hi:[1,0]
	v_pk_add_f32 v[232:233], v[232:233], 1.0 op_sel_hi:[1,0]
	v_pk_add_f32 v[234:235], v[234:235], 1.0 op_sel_hi:[1,0]
	v_pk_add_f32 v[236:237], v[236:237], 1.0 op_sel_hi:[1,0]
	v_pk_add_f32 v[238:239], v[238:239], 1.0 op_sel_hi:[1,0]
	v_pk_add_f32 v[240:241], v[240:241], 1.0 op_sel_hi:[1,0]
	v_pk_add_f32 v[242:243], v[242:243], 1.0 op_sel_hi:[1,0]
	v_pk_mul_f32 v[58:59], v[58:59], v[62:63]
	v_pk_mul_f32 v[60:61], v[60:61], v[64:65]
	v_pk_mul_f32 v[50:51], v[50:51], v[54:55]
	v_pk_mul_f32 v[52:53], v[52:53], v[56:57]
	v_pk_mul_f32 v[42:43], v[42:43], v[46:47]
	v_pk_mul_f32 v[44:45], v[44:45], v[48:49]
	v_pk_mul_f32 v[34:35], v[34:35], v[38:39]
	v_pk_mul_f32 v[36:37], v[36:37], v[40:41]
	v_rcp_f32_e32 v228, v228
	v_rcp_f32_e32 v229, v229
	v_rcp_f32_e32 v230, v230
	v_rcp_f32_e32 v231, v231
	v_rcp_f32_e32 v232, v232
	v_rcp_f32_e32 v233, v233
	v_rcp_f32_e32 v234, v234
	v_rcp_f32_e32 v235, v235
	v_rcp_f32_e32 v236, v236
	v_rcp_f32_e32 v237, v237
	v_rcp_f32_e32 v238, v238
	v_rcp_f32_e32 v239, v239
	v_rcp_f32_e32 v240, v240
	v_rcp_f32_e32 v241, v241
	v_rcp_f32_e32 v242, v242
	v_rcp_f32_e32 v243, v243
	v_pk_mul_f32 v[228:229], v[184:185], v[228:229] op_sel:[1,0] op_sel_hi:[1,1]
	v_pk_mul_f32 v[230:231], v[184:185], v[230:231] op_sel:[1,0] op_sel_hi:[1,1]
	v_pk_mul_f32 v[232:233], v[184:185], v[232:233] op_sel:[1,0] op_sel_hi:[1,1]
	v_pk_mul_f32 v[234:235], v[184:185], v[234:235] op_sel:[1,0] op_sel_hi:[1,1]
	v_pk_mul_f32 v[236:237], v[186:187], v[236:237] op_sel:[1,0] op_sel_hi:[1,1]
	v_pk_mul_f32 v[238:239], v[186:187], v[238:239] op_sel:[1,0] op_sel_hi:[1,1]
	v_pk_mul_f32 v[240:241], v[186:187], v[240:241] op_sel:[1,0] op_sel_hi:[1,1]
	v_pk_mul_f32 v[242:243], v[186:187], v[242:243] op_sel:[1,0] op_sel_hi:[1,1]
	v_pk_mul_f32 v[228:229], v[58:59], v[228:229]
	v_pk_mul_f32 v[230:231], v[60:61], v[230:231]
	v_pk_mul_f32 v[232:233], v[50:51], v[232:233]
	v_pk_mul_f32 v[234:235], v[52:53], v[234:235]
	v_pk_mul_f32 v[236:237], v[42:43], v[236:237]
	v_pk_mul_f32 v[238:239], v[44:45], v[238:239]
	v_pk_mul_f32 v[240:241], v[34:35], v[240:241]
	v_pk_mul_f32 v[242:243], v[36:37], v[242:243]
	v_add_u32_e32 v218, 0xb0000, v161
	v_add_u32_e32 v219, 0xc6000, v161
	v_cvt_pk_bf16_f32 v244, v228, v229
	v_cvt_pk_bf16_f32 v245, v230, v231
	v_cvt_pk_bf16_f32 v246, v232, v233
	v_cvt_pk_bf16_f32 v247, v234, v235
	v_cvt_pk_bf16_f32 v214, v236, v237
	v_cvt_pk_bf16_f32 v215, v238, v239
	v_cvt_pk_bf16_f32 v216, v240, v241
	v_cvt_pk_bf16_f32 v217, v242, v243
	global_store_dwordx4 v218, v[244:247], s[8:9]
	global_store_dwordx4 v219, v[214:217], s[8:9]
	v_pk_mul_f32 v[228:229], v[26:27], v[188:189] op_sel_hi:[1,0]
	v_pk_mul_f32 v[230:231], v[28:29], v[188:189] op_sel_hi:[1,0]
	v_pk_mul_f32 v[232:233], v[18:19], v[188:189] op_sel_hi:[1,0]
	v_pk_mul_f32 v[234:235], v[20:21], v[188:189] op_sel_hi:[1,0]
	v_pk_mul_f32 v[236:237], v[10:11], v[190:191] op_sel_hi:[1,0]
	v_pk_mul_f32 v[238:239], v[12:13], v[190:191] op_sel_hi:[1,0]
	v_pk_mul_f32 v[240:241], v[6:7], v[190:191] op_sel_hi:[1,0]
	v_pk_mul_f32 v[242:243], v[8:9], v[190:191] op_sel_hi:[1,0]
	v_exp_f32_e32 v228, v228
	v_exp_f32_e32 v229, v229
	v_exp_f32_e32 v230, v230
	v_exp_f32_e32 v231, v231
	v_exp_f32_e32 v232, v232
	v_exp_f32_e32 v233, v233
	v_exp_f32_e32 v234, v234
	v_exp_f32_e32 v235, v235
	v_exp_f32_e32 v236, v236
	v_exp_f32_e32 v237, v237
	v_exp_f32_e32 v238, v238
	v_exp_f32_e32 v239, v239
	v_exp_f32_e32 v240, v240
	v_exp_f32_e32 v241, v241
	v_exp_f32_e32 v242, v242
	v_exp_f32_e32 v243, v243
	v_pk_add_f32 v[228:229], v[228:229], 1.0 op_sel_hi:[1,0]
	v_pk_add_f32 v[230:231], v[230:231], 1.0 op_sel_hi:[1,0]
	v_pk_add_f32 v[232:233], v[232:233], 1.0 op_sel_hi:[1,0]
	v_pk_add_f32 v[234:235], v[234:235], 1.0 op_sel_hi:[1,0]
	v_pk_add_f32 v[236:237], v[236:237], 1.0 op_sel_hi:[1,0]
	v_pk_add_f32 v[238:239], v[238:239], 1.0 op_sel_hi:[1,0]
	v_pk_add_f32 v[240:241], v[240:241], 1.0 op_sel_hi:[1,0]
	v_pk_add_f32 v[242:243], v[242:243], 1.0 op_sel_hi:[1,0]
	v_pk_mul_f32 v[26:27], v[26:27], v[30:31]
	v_pk_mul_f32 v[28:29], v[28:29], v[32:33]
	v_pk_mul_f32 v[18:19], v[18:19], v[22:23]
	v_pk_mul_f32 v[20:21], v[20:21], v[24:25]
	v_pk_mul_f32 v[10:11], v[10:11], v[14:15]
	v_pk_mul_f32 v[12:13], v[12:13], v[16:17]
	v_pk_mul_f32 v[6:7], v[6:7], v[2:3]
	v_pk_mul_f32 v[8:9], v[8:9], v[4:5]
	v_rcp_f32_e32 v228, v228
	v_rcp_f32_e32 v229, v229
	v_rcp_f32_e32 v230, v230
	v_rcp_f32_e32 v231, v231
	v_rcp_f32_e32 v232, v232
	v_rcp_f32_e32 v233, v233
	v_rcp_f32_e32 v234, v234
	v_rcp_f32_e32 v235, v235
	v_rcp_f32_e32 v236, v236
	v_rcp_f32_e32 v237, v237
	v_rcp_f32_e32 v238, v238
	v_rcp_f32_e32 v239, v239
	v_rcp_f32_e32 v240, v240
	v_rcp_f32_e32 v241, v241
	v_rcp_f32_e32 v242, v242
	v_rcp_f32_e32 v243, v243
	v_pk_mul_f32 v[228:229], v[188:189], v[228:229] op_sel:[1,0] op_sel_hi:[1,1]
	v_pk_mul_f32 v[230:231], v[188:189], v[230:231] op_sel:[1,0] op_sel_hi:[1,1]
	v_pk_mul_f32 v[232:233], v[188:189], v[232:233] op_sel:[1,0] op_sel_hi:[1,1]
	v_pk_mul_f32 v[234:235], v[188:189], v[234:235] op_sel:[1,0] op_sel_hi:[1,1]
	v_pk_mul_f32 v[236:237], v[190:191], v[236:237] op_sel:[1,0] op_sel_hi:[1,1]
	v_pk_mul_f32 v[238:239], v[190:191], v[238:239] op_sel:[1,0] op_sel_hi:[1,1]
	v_pk_mul_f32 v[240:241], v[190:191], v[240:241] op_sel:[1,0] op_sel_hi:[1,1]
	v_pk_mul_f32 v[242:243], v[190:191], v[242:243] op_sel:[1,0] op_sel_hi:[1,1]
	v_pk_mul_f32 v[228:229], v[26:27], v[228:229]
	v_pk_mul_f32 v[230:231], v[28:29], v[230:231]
	v_pk_mul_f32 v[232:233], v[18:19], v[232:233]
	v_pk_mul_f32 v[234:235], v[20:21], v[234:235]
	v_pk_mul_f32 v[236:237], v[10:11], v[236:237]
	v_pk_mul_f32 v[238:239], v[12:13], v[238:239]
	v_pk_mul_f32 v[240:241], v[6:7], v[240:241]
	v_pk_mul_f32 v[242:243], v[8:9], v[242:243]
	v_add_u32_e32 v218, 0xdc000, v161
	v_add_u32_e32 v219, 0xf2000, v161
	v_cvt_pk_bf16_f32 v244, v228, v229
	v_cvt_pk_bf16_f32 v245, v230, v231
	v_cvt_pk_bf16_f32 v246, v232, v233
	v_cvt_pk_bf16_f32 v247, v234, v235
	v_cvt_pk_bf16_f32 v214, v236, v237
	v_cvt_pk_bf16_f32 v215, v238, v239
	v_cvt_pk_bf16_f32 v216, v240, v241
	v_cvt_pk_bf16_f32 v217, v242, v243
	global_store_dwordx4 v218, v[244:247], s[8:9]
	global_store_dwordx4 v219, v[214:217], s[8:9]
	s_mov_b64 s[2:3], -1
	s_andn2_b64 vcc, exec, s[38:39]
	s_cbranch_vccnz .LBB0_1099
	s_andn2_b64 vcc, exec, s[6:7]
	s_cbranch_vccnz .LBB0_1098
	s_barrier
	s_branch .LBB0_1098
